# MoBA k-mean staging loop: the 8 global loads of an iteration are issued before the first wait instead of in three waited groups
# baseline (speedup 1.0000x reference)
; __device__ void moba_item(const P& p, int bh, int qt, char* smem) {
;     ...
;   {
;     const float* kp = (const float*)(ws + OFF_KPART);
;     for (int e = tid; e < qblk * 128; e += 256) {
;       const int n = e >> 7, d = e & 127;
;       float sm = 0.f;
; #pragma unroll
;       for (int x4 = 0; x4 < 4; ++x4) sm += kp[((size_t)(b * 64 + n * 4 + x4) * 4 + hd) * 128 + d];
;       sKm[n * 132 + d] = sm * (1.f / 256.f);
;     }
.LBB0_462:
	v_ashrrev_i32_e32 v3, 7, v22
	v_ashrrev_i32_e32 v27, 7, v23
	v_lshl_add_u32 v30, v3, 2, s11
	v_lshl_add_u32 v28, v27, 2, s24
	v_mov_b32_e32 v42, v30
	v_ashrrev_i32_e32 v43, 31, v42
	v_lshlrev_b64 v[42:43], 11, v[42:43]
	v_lshl_add_u64 v[42:43], v[20:21], 0, v[42:43]
	v_mov_b32_e32 v44, v28
	v_ashrrev_i32_e32 v45, 31, v44
	v_lshlrev_b64 v[44:45], 11, v[44:45]
	v_lshl_add_u64 v[44:45], v[20:21], 0, v[44:45]
	global_load_dword v34, v[42:43], off
	global_load_dword v35, v[44:45], off
	v_or_b32_e32 v46, 1, v30
	v_ashrrev_i32_e32 v47, 31, v46
	v_lshlrev_b64 v[46:47], 11, v[46:47]
	v_lshl_add_u64 v[46:47], v[20:21], 0, v[46:47]
	v_or_b32_e32 v48, 1, v28
	v_ashrrev_i32_e32 v49, 31, v48
	v_lshlrev_b64 v[48:49], 11, v[48:49]
	v_lshl_add_u64 v[48:49], v[20:21], 0, v[48:49]
	global_load_dword v36, v[46:47], off
	global_load_dword v37, v[48:49], off
	v_or_b32_e32 v50, 2, v30
	v_ashrrev_i32_e32 v51, 31, v50
	v_lshlrev_b64 v[50:51], 11, v[50:51]
	v_lshl_add_u64 v[50:51], v[20:21], 0, v[50:51]
	v_or_b32_e32 v52, 2, v28
	v_ashrrev_i32_e32 v53, 31, v52
	v_lshlrev_b64 v[52:53], 11, v[52:53]
	v_lshl_add_u64 v[52:53], v[20:21], 0, v[52:53]
	global_load_dword v38, v[50:51], off
	global_load_dword v39, v[52:53], off
	v_or_b32_e32 v54, 3, v30
	v_ashrrev_i32_e32 v55, 31, v54
	v_lshlrev_b64 v[54:55], 11, v[54:55]
	v_lshl_add_u64 v[54:55], v[20:21], 0, v[54:55]
	v_or_b32_e32 v56, 3, v28
	v_ashrrev_i32_e32 v57, 31, v56
	v_lshlrev_b64 v[56:57], 11, v[56:57]
	v_lshl_add_u64 v[56:57], v[20:21], 0, v[56:57]
	global_load_dword v40, v[54:55], off
	global_load_dword v41, v[56:57], off
	v_add_u32_e32 v26, -2, v26
	s_mov_b32 s26, 0x3b800000
	v_cmp_eq_u32_e32 vcc, 0, v26
	v_add_u32_e32 v23, 0x200, v23
	v_add_u32_e32 v22, 0x200, v22
	s_or_b64 s[8:9], vcc, s[8:9]
	s_waitcnt vmcnt(6)
	v_pk_add_f32 v[32:33], v[34:35], 0 op_sel_hi:[1,0]
	s_waitcnt vmcnt(4)
	v_pk_add_f32 v[32:33], v[32:33], v[36:37]
	s_waitcnt vmcnt(2)
	v_pk_add_f32 v[32:33], v[32:33], v[38:39]
	s_waitcnt vmcnt(0)
	v_pk_add_f32 v[28:29], v[32:33], v[40:41]
	s_nop 0
	v_pk_mul_f32 v[28:29], v[28:29], s[26:27] op_sel_hi:[1,0]
	v_mad_u64_u32 v[30:31], s[26:27], v3, s25, v[0:1]
	v_mad_u64_u32 v[32:33], s[26:27], v27, s25, v[0:1]
	ds_write_b32 v30, v28 offset:37120
	ds_write_b32 v32, v29 offset:37120
	s_andn2_b64 exec, exec, s[8:9]
	s_cbranch_execnz .LBB0_462
	s_or_b64 exec, exec, s[8:9]
	v_cmp_ne_u32_e32 vcc, v24, v25
	v_lshl_add_u32 v22, v25, 8, v2
	s_orn2_b64 s[8:9], vcc, exec
